# latent attention key loop: static s_setprio 1 for waves 4-7 (younger half), reset after the loop
# baseline (speedup 1.0000x reference)
.LBB0_370:
	s_or_b64 exec, exec, s[2:3]
	s_lshl_b32 s44, s17, 6
	v_or_b32_e32 v0, s44, v147
	v_mul_u32_u24_e32 v0, 0x3400, v0
	v_readlane_b32 s2, v250, 6
	v_lshlrev_b32_e32 v0, 1, v0
	v_readlane_b32 s3, v250, 7
	s_ashr_i32 s17, s16, 31
	v_lshlrev_b32_e32 v118, 1, v122
	v_lshl_add_u64 v[142:143], s[2:3], 0, v[0:1]
	v_lshl_add_u64 v[94:95], s[16:17], 1, v[142:143]
	v_mov_b32_e32 v119, v1
	v_lshl_add_u64 v[94:95], v[94:95], 0, v[118:119]
	global_load_dwordx4 v[94:97], v[94:95], off
	s_waitcnt vmcnt(0)
	ds_write_b128 v157, v[70:73]
	s_and_saveexec_b64 s[2:3], s[0:1]
	ds_write_b128 v158, v[66:69]
	s_or_b64 exec, exec, s[2:3]
	s_waitcnt lgkmcnt(0)
	v_add_f32_e32 v0, v167, v168
	v_fmamk_f32 v0, v0, 0x3c2aaaab, v248
	v_rsq_f32_e32 v0, v0
	s_mov_b32 s15, s4
	s_addk_i32 s45, 0x2800
	s_mov_b32 s17, 0
	v_mul_f32_e32 v0, 0x3e16c740, v0
	v_mul_f32_e32 v39, v39, v0
	v_mul_f32_e32 v38, v38, v0
	v_mul_f32_e32 v70, v40, v0
	v_mul_f32_e32 v40, v39, v163
	v_mul_f32_e32 v39, v41, v0
	v_mul_f32_e32 v34, v34, v0
	v_mul_f32_e32 v35, v35, v0
	v_mul_f32_e32 v38, v38, v162
	v_mul_f32_e32 v72, v39, v161
	v_mul_f32_e32 v34, v34, v160
	v_mul_f32_e32 v160, v35, v127
	v_mul_f32_e32 v35, v36, v0
	v_mul_f32_e32 v30, v30, v0
	v_pk_mul_f32 v[40:41], v[14:15], v[40:41] op_sel:[1,0] op_sel_hi:[0,0]
	v_mul_f32_e32 v70, v70, v164
	v_mul_f32_e32 v36, v35, v125
	v_mul_f32_e32 v35, v37, v0
	v_mul_f32_e32 v30, v30, v166
	v_mul_f32_e32 v31, v31, v0
	v_pk_fma_f32 v[166:167], v[14:15], v[38:39], v[40:41] neg_lo:[0,0,1] neg_hi:[0,0,1]
	v_pk_fma_f32 v[14:15], v[14:15], v[38:39], v[40:41] op_sel_hi:[1,0,1]
	v_pk_mul_f32 v[38:39], v[16:17], v[72:73] op_sel:[1,0] op_sel_hi:[0,0]
	v_mul_f32_e32 v162, v35, v113
	v_mul_f32_e32 v164, v31, v165
	v_mul_f32_e32 v31, v32, v0
	v_pk_fma_f32 v[40:41], v[16:17], v[70:71], v[38:39] neg_lo:[0,0,1] neg_hi:[0,0,1]
	v_pk_fma_f32 v[16:17], v[16:17], v[70:71], v[38:39] op_sel_hi:[1,0,1]
	v_pk_mul_f32 v[38:39], v[160:161], v[10:11] op_sel:[0,1] op_sel_hi:[0,0]
	v_mul_f32_e32 v32, v31, v79
	v_mul_f32_e32 v31, v33, v0
	v_mul_f32_e32 v27, v27, v0
	v_pk_fma_f32 v[160:161], v[34:35], v[10:11], v[38:39] neg_lo:[0,0,1] neg_hi:[0,0,1]
	v_pk_fma_f32 v[10:11], v[34:35], v[10:11], v[38:39] op_sel_hi:[0,1,1]
	v_pk_mul_f32 v[34:35], v[162:163], v[12:13] op_sel:[0,1] op_sel_hi:[0,0]
	v_mul_f32_e32 v78, v31, v78
	v_mul_f32_e32 v76, v27, v76
	v_mul_f32_e32 v27, v28, v0
	v_pk_fma_f32 v[38:39], v[36:37], v[12:13], v[34:35] neg_lo:[0,0,1] neg_hi:[0,0,1]
	v_pk_fma_f32 v[12:13], v[36:37], v[12:13], v[34:35] op_sel_hi:[0,1,1]
	v_pk_mul_f32 v[34:35], v[164:165], v[6:7] op_sel:[0,1] op_sel_hi:[0,0]
	v_mul_f32_e32 v26, v26, v0
	v_mul_f32_e32 v28, v27, v75
	v_mul_f32_e32 v27, v29, v0
	v_pk_fma_f32 v[36:37], v[30:31], v[6:7], v[34:35] neg_lo:[0,0,1] neg_hi:[0,0,1]
	v_pk_fma_f32 v[6:7], v[30:31], v[6:7], v[34:35] op_sel_hi:[0,1,1]
	v_pk_mul_f32 v[30:31], v[78:79], v[8:9] op_sel:[0,1] op_sel_hi:[0,0]
	v_mul_f32_e32 v26, v26, v77
	v_mul_f32_e32 v74, v27, v74
	v_pk_fma_f32 v[34:35], v[32:33], v[8:9], v[30:31] neg_lo:[0,0,1] neg_hi:[0,0,1]
	v_pk_fma_f32 v[8:9], v[32:33], v[8:9], v[30:31] op_sel_hi:[0,1,1]
	v_pk_mul_f32 v[30:31], v[76:77], v[2:3] op_sel:[0,1] op_sel_hi:[0,0]
	v_pk_fma_f32 v[32:33], v[26:27], v[2:3], v[30:31] neg_lo:[0,0,1] neg_hi:[0,0,1]
	v_pk_fma_f32 v[2:3], v[26:27], v[2:3], v[30:31] op_sel_hi:[0,1,1]
	v_pk_mul_f32 v[26:27], v[74:75], v[4:5] op_sel:[0,1] op_sel_hi:[0,0]
	v_pk_fma_f32 v[30:31], v[28:29], v[4:5], v[26:27] neg_lo:[0,0,1] neg_hi:[0,0,1]
	v_pk_fma_f32 v[4:5], v[28:29], v[4:5], v[26:27] op_sel_hi:[0,1,1]
	v_pk_mul_f32 v[24:25], v[24:25], v[0:1] op_sel_hi:[1,0]
	v_pk_mul_f32 v[22:23], v[22:23], v[0:1] op_sel_hi:[1,0]
	v_pk_mul_f32 v[20:21], v[20:21], v[0:1] op_sel_hi:[1,0]
	v_pk_mul_f32 v[18:19], v[18:19], v[0:1] op_sel_hi:[1,0]
	v_pk_mul_f32 v[26:27], v[48:49], v[0:1] op_sel_hi:[1,0]
	v_pk_mul_f32 v[28:29], v[46:47], v[0:1] op_sel_hi:[1,0]
	v_pk_mul_f32 v[44:45], v[44:45], v[0:1] op_sel_hi:[1,0]
	v_pk_mul_f32 v[42:43], v[42:43], v[0:1] op_sel_hi:[1,0]
	v_pk_mul_f32 v[46:47], v[56:57], v[0:1] op_sel_hi:[1,0]
	v_pk_mul_f32 v[48:49], v[54:55], v[0:1] op_sel_hi:[1,0]
	v_pk_mul_f32 v[52:53], v[52:53], v[0:1] op_sel_hi:[1,0]
	v_pk_mul_f32 v[50:51], v[50:51], v[0:1] op_sel_hi:[1,0]
	v_pk_mul_f32 v[54:55], v[64:65], v[0:1] op_sel_hi:[1,0]
	v_pk_mul_f32 v[56:57], v[62:63], v[0:1] op_sel_hi:[1,0]
	v_pk_mul_f32 v[60:61], v[60:61], v[0:1] op_sel_hi:[1,0]
	v_pk_mul_f32 v[58:59], v[58:59], v[0:1] op_sel_hi:[1,0]
	v_pk_mul_f32 v[24:25], v[24:25], v[80:81]
	v_pk_mul_f32 v[22:23], v[22:23], v[82:83]
	v_pk_mul_f32 v[20:21], v[20:21], v[84:85]
	v_pk_mul_f32 v[18:19], v[18:19], v[86:87]
	v_pk_mul_f32 v[26:27], v[26:27], v[88:89]
	v_pk_mul_f32 v[28:29], v[28:29], v[90:91]
	v_pk_mul_f32 v[44:45], v[44:45], v[92:93]
	v_pk_mul_f32 v[42:43], v[42:43], v[98:99]
	v_pk_mul_f32 v[46:47], v[46:47], v[100:101]
	v_pk_mul_f32 v[48:49], v[48:49], v[128:129]
	v_pk_mul_f32 v[52:53], v[52:53], v[130:131]
	v_pk_mul_f32 v[50:51], v[50:51], v[132:133]
	v_pk_mul_f32 v[54:55], v[54:55], v[134:135]
	v_pk_mul_f32 v[56:57], v[56:57], v[136:137]
	v_pk_mul_f32 v[60:61], v[60:61], v[138:139]
	v_pk_mul_f32 v[58:59], v[58:59], v[140:141]
	v_mov_b32_e32 v113, 0
	v_cvt_pk_bf16_f32 v70, v58, v59
	v_cvt_pk_bf16_f32 v71, v60, v61
	v_cvt_pk_bf16_f32 v72, v56, v57
	v_cvt_pk_bf16_f32 v73, v54, v55
	v_cvt_pk_bf16_f32 v74, v50, v51
	v_cvt_pk_bf16_f32 v75, v52, v53
	v_cvt_pk_bf16_f32 v76, v48, v49
	v_cvt_pk_bf16_f32 v77, v46, v47
	v_cvt_pk_bf16_f32 v78, v42, v43
	v_cvt_pk_bf16_f32 v79, v44, v45
	v_cvt_pk_bf16_f32 v80, v28, v29
	v_cvt_pk_bf16_f32 v81, v26, v27
	v_cvt_pk_bf16_f32 v82, v18, v19
	v_cvt_pk_bf16_f32 v83, v20, v21
	v_cvt_pk_bf16_f32 v84, v22, v23
	v_cvt_pk_bf16_f32 v85, v24, v25
	v_cvt_pk_bf16_f32 v86, v166, v15
	v_cvt_pk_bf16_f32 v87, v40, v17
	v_cvt_pk_bf16_f32 v88, v160, v11
	v_cvt_pk_bf16_f32 v89, v38, v13
	v_cvt_pk_bf16_f32 v90, v36, v7
	v_cvt_pk_bf16_f32 v91, v34, v9
	v_cvt_pk_bf16_f32 v92, v32, v3
	v_cvt_pk_bf16_f32 v93, v30, v5
	v_lshl_add_u64 v[64:65], v[106:107], 0, s[14:15]
	v_lshl_add_u64 v[128:129], v[110:111], 0, s[14:15]
	v_lshl_add_u64 v[130:131], v[142:143], 0, v[118:119]
	v_mov_b32_e32 v117, 0xf149f2ca
	s_mov_b32 s16, s38
	v_mov_b32_e32 v16, 0
	v_mov_b32_e32 v17, v113
	v_mov_b32_e32 v18, v113
	v_mov_b32_e32 v19, v113
	v_mov_b32_e32 v20, v113
	v_mov_b32_e32 v21, v113
	v_mov_b32_e32 v22, v113
	v_mov_b32_e32 v23, v113
	v_mov_b32_e32 v24, v113
	v_mov_b32_e32 v25, v113
	v_mov_b32_e32 v26, v113
	v_mov_b32_e32 v27, v113
	v_mov_b32_e32 v28, v113
	v_mov_b32_e32 v29, v113
	v_mov_b32_e32 v30, v113
	v_mov_b32_e32 v31, v113
	v_mov_b32_e32 v32, 0
	v_mov_b32_e32 v33, v113
	v_mov_b32_e32 v34, v113
	v_mov_b32_e32 v35, v113
	v_mov_b32_e32 v36, v113
	v_mov_b32_e32 v37, v113
	v_mov_b32_e32 v38, v113
	v_mov_b32_e32 v39, v113
	v_mov_b32_e32 v40, v113
	v_mov_b32_e32 v41, v113
	v_mov_b32_e32 v42, v113
	v_mov_b32_e32 v43, v113
	v_mov_b32_e32 v44, v113
	v_mov_b32_e32 v45, v113
	v_mov_b32_e32 v46, v113
	v_mov_b32_e32 v47, v113
	ds_write_b128 v159, v[94:97] offset:6656
	s_waitcnt lgkmcnt(0)
	s_barrier
	s_cmp_lt_u32 s27, 4
	s_cbranch_scc1 .Lattn_prio_skip
	s_setprio 1
.Lattn_prio_skip:
.LBB0_373:
	s_add_i32 s2, s19, s17
	s_cmp_lt_i32 s2, 63
	s_cselect_b32 s2, s13, s45
	s_add_i32 s2, s16, s2
	v_add_u32_e32 v0, s2, v145
	v_mad_i64_i32 v[2:3], s[14:15], v0, s48, v[64:65]
	global_load_dwordx4 v[98:101], v[2:3], off
	s_and_saveexec_b64 s[14:15], s[0:1]
	s_cbranch_execz .LBB0_375
	v_add_u32_e32 v0, s2, v146
	v_mad_i64_i32 v[2:3], s[34:35], v0, s48, v[128:129]
	global_load_dwordx4 v[66:69], v[2:3], off

.LBB0_381:
	s_setprio 0
	s_andn2_b64 vcc, exec, s[10:11]
	s_waitcnt lgkmcnt(0)
	s_barrier
	s_cbranch_vccnz .LBB0_367
	ds_read2st64_b32 v[2:3], v123 offset0:224 offset1:225
	v_max_f32_e32 v5, v0, v0
	s_ashr_i32 s13, s12, 31
	s_waitcnt lgkmcnt(0)
	v_max_f32_e32 v6, v2, v2
	v_max_f32_e32 v5, v5, v6
	v_sub_f32_e32 v0, v0, v5
	v_sub_f32_e32 v5, v2, v5
	v_exp_f32_e32 v2, v0
	v_exp_f32_e32 v5, v5
	ds_read2st64_b32 v[6:7], v123 offset0:192 offset1:193
	ds_read2st64_b32 v[8:9], v123 offset0:194 offset1:195
	ds_read2st64_b32 v[10:11], v123 offset0:196 offset1:197
	ds_read2st64_b32 v[12:13], v123 offset0:198 offset1:199
	ds_read2st64_b32 v[14:15], v123 offset0:208 offset1:209
	ds_read2st64_b32 v[48:49], v123 offset0:210 offset1:211
	ds_read2st64_b32 v[50:51], v123 offset0:212 offset1:213
	ds_read2st64_b32 v[52:53], v123 offset0:214 offset1:215
	v_pk_mul_f32 v[54:55], v[4:5], v[2:3]
	s_nop 0
	v_add_f32_e32 v0, v54, v55
	ds_bpermute_b32 v3, v103, v0
	ds_read2st64_b32 v[54:55], v123 offset0:200 offset1:201
	ds_read2st64_b32 v[56:57], v123 offset0:202 offset1:203
	ds_read2st64_b32 v[58:59], v123 offset0:204 offset1:205
	ds_read2st64_b32 v[60:61], v123 offset0:206 offset1:207
	ds_read2st64_b32 v[62:63], v123 offset0:216 offset1:217
	ds_read2st64_b32 v[64:65], v123 offset0:218 offset1:219
	ds_read2st64_b32 v[66:67], v123 offset0:220 offset1:221
	ds_read2st64_b32 v[68:69], v123 offset0:222 offset1:223
	s_waitcnt lgkmcnt(8)
	v_add_f32_e32 v0, v0, v3
	v_div_scale_f32 v3, s[2:3], v0, v0, 1.0
	v_rcp_f32_e32 v4, v3
	v_readlane_b32 s2, v253, 6
	v_readlane_b32 s3, v253, 7
	v_fma_f32 v70, -v3, v4, 1.0
	v_fmac_f32_e32 v4, v70, v4
	v_div_scale_f32 v70, vcc, 1.0, v0, 1.0
	v_mul_f32_e32 v71, v70, v4
	v_fma_f32 v72, -v3, v71, v70
	v_fmac_f32_e32 v71, v72, v4
	v_fma_f32 v3, -v3, v71, v70
	v_div_fmas_f32 v3, v3, v4, v71
	v_lshl_add_u64 v[70:71], s[12:13], 0, v[108:109]
	v_lshlrev_b64 v[70:71], 10, v[70:71]
	v_lshl_add_u64 v[70:71], s[2:3], 0, v[70:71]
	s_lshl_b32 s2, s44, 1
	s_mov_b32 s3, s4
	v_div_fixup_f32 v4, v3, v0, 1.0
	v_lshl_add_u64 v[70:71], v[70:71], 0, s[2:3]
	v_lshlrev_b32_e32 v0, 1, v124
	v_lshl_add_u64 v[70:71], v[70:71], 0, v[0:1]
	v_mov_b32_e32 v0, v5
	v_pk_mul_f32 v[6:7], v[6:7], v[0:1] op_sel_hi:[1,0]
	v_pk_mul_f32 v[8:9], v[0:1], v[8:9] op_sel_hi:[0,1]
	v_pk_fma_f32 v[6:7], v[32:33], v[2:3], v[6:7] op_sel_hi:[1,0,1]
	v_pk_fma_f32 v[8:9], v[34:35], v[2:3], v[8:9] op_sel_hi:[1,0,1]
	v_pk_mul_f32 v[6:7], v[6:7], v[4:5] op_sel_hi:[1,0]
	v_pk_mul_f32 v[8:9], v[8:9], v[4:5] op_sel_hi:[1,0]
	v_cvt_pk_bf16_f32 v6, v6, v7
	v_cvt_pk_bf16_f32 v7, v8, v9
	global_store_dwordx2 v[70:71], v[6:7], off
	v_pk_mul_f32 v[6:7], v[14:15], v[0:1] op_sel_hi:[1,0]
	v_pk_mul_f32 v[8:9], v[0:1], v[48:49] op_sel_hi:[0,1]
	v_pk_fma_f32 v[6:7], v[16:17], v[2:3], v[6:7] op_sel_hi:[1,0,1]
	v_pk_fma_f32 v[8:9], v[18:19], v[2:3], v[8:9] op_sel_hi:[1,0,1]
	v_pk_mul_f32 v[6:7], v[6:7], v[4:5] op_sel_hi:[1,0]
	v_pk_mul_f32 v[8:9], v[8:9], v[4:5] op_sel_hi:[1,0]
	v_cvt_pk_bf16_f32 v6, v6, v7
	v_cvt_pk_bf16_f32 v7, v8, v9
	global_store_dwordx2 v[70:71], v[6:7], off offset:64
	v_pk_mul_f32 v[6:7], v[0:1], v[10:11] op_sel_hi:[0,1]
	v_pk_mul_f32 v[8:9], v[0:1], v[12:13] op_sel_hi:[0,1]
	v_pk_fma_f32 v[6:7], v[36:37], v[2:3], v[6:7] op_sel_hi:[1,0,1]
	v_pk_fma_f32 v[8:9], v[38:39], v[2:3], v[8:9] op_sel_hi:[1,0,1]
	v_pk_mul_f32 v[6:7], v[6:7], v[4:5] op_sel_hi:[1,0]
	v_pk_mul_f32 v[8:9], v[8:9], v[4:5] op_sel_hi:[1,0]
	v_cvt_pk_bf16_f32 v6, v6, v7
	v_cvt_pk_bf16_f32 v7, v8, v9
	global_store_dwordx2 v[70:71], v[6:7], off offset:16
	v_pk_mul_f32 v[6:7], v[0:1], v[50:51] op_sel_hi:[0,1]
	v_pk_mul_f32 v[8:9], v[0:1], v[52:53] op_sel_hi:[0,1]
	v_pk_fma_f32 v[6:7], v[20:21], v[2:3], v[6:7] op_sel_hi:[1,0,1]
	v_pk_fma_f32 v[8:9], v[22:23], v[2:3], v[8:9] op_sel_hi:[1,0,1]
	v_pk_mul_f32 v[6:7], v[6:7], v[4:5] op_sel_hi:[1,0]
	v_pk_mul_f32 v[8:9], v[8:9], v[4:5] op_sel_hi:[1,0]
	v_cvt_pk_bf16_f32 v6, v6, v7
	v_cvt_pk_bf16_f32 v7, v8, v9
	global_store_dwordx2 v[70:71], v[6:7], off offset:80
	s_waitcnt lgkmcnt(7)
	v_pk_mul_f32 v[6:7], v[0:1], v[54:55] op_sel_hi:[0,1]
	s_waitcnt lgkmcnt(6)
	v_pk_mul_f32 v[8:9], v[0:1], v[56:57] op_sel_hi:[0,1]
	v_pk_fma_f32 v[6:7], v[40:41], v[2:3], v[6:7] op_sel_hi:[1,0,1]
	v_pk_fma_f32 v[8:9], v[42:43], v[2:3], v[8:9] op_sel_hi:[1,0,1]
	v_pk_mul_f32 v[6:7], v[6:7], v[4:5] op_sel_hi:[1,0]
	v_pk_mul_f32 v[8:9], v[8:9], v[4:5] op_sel_hi:[1,0]
	v_cvt_pk_bf16_f32 v6, v6, v7
	v_cvt_pk_bf16_f32 v7, v8, v9
	global_store_dwordx2 v[70:71], v[6:7], off offset:32
	s_waitcnt lgkmcnt(3)
	v_pk_mul_f32 v[6:7], v[0:1], v[62:63] op_sel_hi:[0,1]
	s_waitcnt lgkmcnt(2)
	v_pk_mul_f32 v[8:9], v[0:1], v[64:65] op_sel_hi:[0,1]
	v_pk_fma_f32 v[6:7], v[24:25], v[2:3], v[6:7] op_sel_hi:[1,0,1]
	v_pk_fma_f32 v[8:9], v[26:27], v[2:3], v[8:9] op_sel_hi:[1,0,1]
	v_pk_mul_f32 v[6:7], v[6:7], v[4:5] op_sel_hi:[1,0]
	v_pk_mul_f32 v[8:9], v[8:9], v[4:5] op_sel_hi:[1,0]
	v_cvt_pk_bf16_f32 v6, v6, v7
	v_cvt_pk_bf16_f32 v7, v8, v9
	global_store_dwordx2 v[70:71], v[6:7], off offset:96
	v_pk_mul_f32 v[6:7], v[0:1], v[58:59] op_sel_hi:[0,1]
	v_pk_mul_f32 v[8:9], v[0:1], v[60:61] op_sel_hi:[0,1]
	v_pk_fma_f32 v[6:7], v[44:45], v[2:3], v[6:7] op_sel_hi:[1,0,1]
	v_pk_fma_f32 v[8:9], v[46:47], v[2:3], v[8:9] op_sel_hi:[1,0,1]
	v_pk_mul_f32 v[6:7], v[6:7], v[4:5] op_sel_hi:[1,0]
	v_pk_mul_f32 v[8:9], v[8:9], v[4:5] op_sel_hi:[1,0]
	v_cvt_pk_bf16_f32 v6, v6, v7
	v_cvt_pk_bf16_f32 v7, v8, v9
	global_store_dwordx2 v[70:71], v[6:7], off offset:48
	s_waitcnt lgkmcnt(1)
	v_pk_mul_f32 v[6:7], v[0:1], v[66:67] op_sel_hi:[0,1]
	s_waitcnt lgkmcnt(0)
	v_pk_mul_f32 v[8:9], v[0:1], v[68:69] op_sel_hi:[0,1]
	v_pk_fma_f32 v[6:7], v[28:29], v[2:3], v[6:7] op_sel_hi:[1,0,1]
	v_pk_fma_f32 v[2:3], v[30:31], v[2:3], v[8:9] op_sel_hi:[1,0,1]
	v_pk_mul_f32 v[6:7], v[6:7], v[4:5] op_sel_hi:[1,0]
	v_pk_mul_f32 v[2:3], v[2:3], v[4:5] op_sel_hi:[1,0]
	v_cvt_pk_bf16_f32 v6, v6, v7
	v_cvt_pk_bf16_f32 v7, v2, v3
	global_store_dwordx2 v[70:71], v[6:7], off offset:112
	s_branch .LBB0_367
